# residual GEMM epilogues (7 instances): one-dword touch loads of all 16 row groups before the serial load-fma-store chain
# baseline (speedup 1.0000x reference)
; #define EPI_LOOP_ROWS _Pragma("unroll") for (int ai = 0; ai < 2; ++ai) _Pragma("unroll") for (int m = 0; m < 4; ++m)
; #define EPI_LOOP_BJ _Pragma("unroll") for (int bj = 0; bj < 2; ++bj)
;     DI void operator()(const AccT& acc, int brow, int bcol, int wr, int wc, int fr, int fq) const {
;         EPI_LOOP_BJ { const int col = bcol + bj * 128 + wc * 32 + fq * 8;
;             const f32x4 g0 = *(const f32x4*)(gate + col), g1 = *(const f32x4*)(gate + col + 4); f32x4 b0 = (f32x4){0.f, 0.f, 0.f, 0.f}, b1 = b0; if (bias) { b0 = *(const f32x4*)(bias + col); b1 = *(const f32x4*)(bias + col + 4); }
;             EPI_LOOP_ROWS { const size_t eo = (size_t)(ai * 128 + wr * 64 + m * 16 + fr) * D + col; float* q = base + eo;
;                 f32x4 x0 = (f32x4){0.f, 0.f, 0.f, 0.f}, x1 = x0; if (rmw) { x0 = *(const f32x4*)(src + eo); x1 = *(const f32x4*)(src + eo + 4); }
;                 x0 += g0 * (acc[ai][bj][m][0] + b0); x1 += g1 * (acc[ai][bj][m][1] + b1); *(f32x4*)q = x0; *(f32x4*)(q + 4) = x1; } }
; template <int S>
; DI void gemm_resid(const bf16_t* A, const bf16_t* Bt, int K, bool with_ctx, float* out, const float* xin, const float* gate, const float* bias, float* part, char* shm) {
;     ...
;               [&](int L, const AccT& acc, int brow, int bcol, int wr, int wc, int fr, int fq) {
;                   const int b = brow / LT; EpiResid e;
;                   if (L < 256) { const size_t ro = ((size_t)(b * LL + (brow - b * LT) - LC)) * D; e.base = out + ro; e.src = xin + ro; e.gate = gate + (size_t)b * 6144; e.bias = bias; e.rmw = true; }
;                   else { const int s = (L - 256) % S; e.base = part + ((size_t)s * NB * LC + b * LC) * D; e.src = e.base; e.gate = gate + (size_t)8 * 6144; e.bias = s == 0 ? bias : nullptr; e.rmw = false; }
;                   e(acc, brow, bcol, wr, wc, fr, fq); });
.LBB0_857:
	v_lshrrev_b32_e32 v128, 1, v136
	v_and_b32_e32 v129, 0x60, v128
	v_and_b32_e32 v128, 24, v128
	v_add3_u32 v158, v129, s57, v128
	v_ashrrev_i32_e32 v159, 31, v158
	v_lshlrev_b64 v[138:139], 2, v[158:159]
	v_lshl_add_u64 v[160:161], s[4:5], 0, v[138:139]
	global_load_dwordx4 v[128:131], v[160:161], off offset:16
	global_load_dwordx4 v[132:135], v[160:161], off
	v_and_b32_e32 v137, 15, v136
	v_ashrrev_i32_e32 v136, 2, v136
	s_movk_i32 s4, 0xffc0
	v_and_or_b32 v164, v136, s4, v137
	v_ashrrev_i32_e32 v165, 31, v164
	v_lshlrev_b64 v[136:137], 12, v[164:165]
	v_lshl_add_u64 v[162:163], s[38:39], 0, v[136:137]
	v_cndmask_b32_e64 v137, 0, 1, s[14:15]
	v_lshl_add_u64 v[166:167], v[162:163], 0, v[138:139]
	v_mov_b32_e32 v136, 0
	v_cmp_ne_u32_e64 s[4:5], 1, v137
	s_and_b64 vcc, exec, s[14:15]
	s_cbranch_vccz .Lrpf_skip_0
	global_load_dword v172, v[166:167], off
	v_add_co_u32_e32 v188, vcc, 0x10000, v166
	s_nop 1
	v_addc_co_u32_e32 v189, vcc, 0, v167, vcc
	global_load_dword v173, v[188:189], off
	v_add_co_u32_e32 v188, vcc, 0x20000, v166
	s_nop 1
	v_addc_co_u32_e32 v189, vcc, 0, v167, vcc
	global_load_dword v174, v[188:189], off
	v_add_co_u32_e32 v188, vcc, 0x30000, v166
	s_nop 1
	v_addc_co_u32_e32 v189, vcc, 0, v167, vcc
	global_load_dword v175, v[188:189], off
	v_add_co_u32_e32 v188, vcc, 0x80000, v166
	s_nop 1
	v_addc_co_u32_e32 v189, vcc, 0, v167, vcc
	global_load_dword v176, v[188:189], off
	v_add_co_u32_e32 v188, vcc, 0x90000, v166
	s_nop 1
	v_addc_co_u32_e32 v189, vcc, 0, v167, vcc
	global_load_dword v177, v[188:189], off
	v_add_co_u32_e32 v188, vcc, 0xa0000, v166
	s_nop 1
	v_addc_co_u32_e32 v189, vcc, 0, v167, vcc
	global_load_dword v178, v[188:189], off
	v_add_co_u32_e32 v188, vcc, 0xb0000, v166
	s_nop 1
	v_addc_co_u32_e32 v189, vcc, 0, v167, vcc
	global_load_dword v179, v[188:189], off
	v_add_co_u32_e32 v188, vcc, 0x200, v166
	s_nop 1
	v_addc_co_u32_e32 v189, vcc, 0, v167, vcc
	global_load_dword v180, v[188:189], off
	v_add_co_u32_e32 v188, vcc, 0x10200, v166
	s_nop 1
	v_addc_co_u32_e32 v189, vcc, 0, v167, vcc
	global_load_dword v181, v[188:189], off
	v_add_co_u32_e32 v188, vcc, 0x20200, v166
	s_nop 1
	v_addc_co_u32_e32 v189, vcc, 0, v167, vcc
	global_load_dword v182, v[188:189], off
	v_add_co_u32_e32 v188, vcc, 0x30200, v166
	s_nop 1
	v_addc_co_u32_e32 v189, vcc, 0, v167, vcc
	global_load_dword v183, v[188:189], off
	v_add_co_u32_e32 v188, vcc, 0x80200, v166
	s_nop 1
	v_addc_co_u32_e32 v189, vcc, 0, v167, vcc
	global_load_dword v184, v[188:189], off
	v_add_co_u32_e32 v188, vcc, 0x90200, v166
	s_nop 1
	v_addc_co_u32_e32 v189, vcc, 0, v167, vcc
	global_load_dword v185, v[188:189], off
	v_add_co_u32_e32 v188, vcc, 0xa0200, v166
	s_nop 1
	v_addc_co_u32_e32 v189, vcc, 0, v167, vcc
	global_load_dword v186, v[188:189], off
	v_add_co_u32_e32 v188, vcc, 0xb0200, v166
	s_nop 1
	v_addc_co_u32_e32 v189, vcc, 0, v167, vcc
	global_load_dword v187, v[188:189], off
.Lrpf_skip_0:
	s_andn2_b64 vcc, exec, s[14:15]
	v_mov_b32_e32 v142, 0
	v_mov_b32_e32 v143, 0
	v_mov_b32_e32 v144, 0
	v_mov_b32_e32 v145, 0
	v_mov_b32_e32 v138, 0
	v_mov_b32_e32 v139, 0
	v_mov_b32_e32 v140, 0
	v_mov_b32_e32 v141, 0
	s_cbranch_vccnz .LBB0_859
	global_load_dwordx4 v[142:145], v[166:167], off
	global_load_dwordx4 v[138:141], v[166:167], off offset:16

; #define EPI_LOOP_ROWS _Pragma("unroll") for (int ai = 0; ai < 2; ++ai) _Pragma("unroll") for (int m = 0; m < 4; ++m)
; #define EPI_LOOP_BJ _Pragma("unroll") for (int bj = 0; bj < 2; ++bj)
;     DI void operator()(const AccT& acc, int brow, int bcol, int wr, int wc, int fr, int fq) const {
;         EPI_LOOP_BJ { const int col = bcol + bj * 128 + wc * 32 + fq * 8;
;             const f32x4 g0 = *(const f32x4*)(gate + col), g1 = *(const f32x4*)(gate + col + 4); f32x4 b0 = (f32x4){0.f, 0.f, 0.f, 0.f}, b1 = b0; if (bias) { b0 = *(const f32x4*)(bias + col); b1 = *(const f32x4*)(bias + col + 4); }
;             EPI_LOOP_ROWS { const size_t eo = (size_t)(ai * 128 + wr * 64 + m * 16 + fr) * D + col; float* q = base + eo;
;                 f32x4 x0 = (f32x4){0.f, 0.f, 0.f, 0.f}, x1 = x0; if (rmw) { x0 = *(const f32x4*)(src + eo); x1 = *(const f32x4*)(src + eo + 4); }
;                 x0 += g0 * (acc[ai][bj][m][0] + b0); x1 += g1 * (acc[ai][bj][m][1] + b1); *(f32x4*)q = x0; *(f32x4*)(q + 4) = x1; } }
; template <int S>
; DI void gemm_resid(const bf16_t* A, const bf16_t* Bt, int K, bool with_ctx, float* out, const float* xin, const float* gate, const float* bias, float* part, char* shm) {
;     ...
;               [&](int L, const AccT& acc, int brow, int bcol, int wr, int wc, int fr, int fq) {
;                   const int b = brow / LT; EpiResid e;
;                   if (L < 256) { const size_t ro = ((size_t)(b * LL + (brow - b * LT) - LC)) * D; e.base = out + ro; e.src = xin + ro; e.gate = gate + (size_t)b * 6144; e.bias = bias; e.rmw = true; }
;                   else { const int s = (L - 256) % S; e.base = part + ((size_t)s * NB * LC + b * LC) * D; e.src = e.base; e.gate = gate + (size_t)8 * 6144; e.bias = s == 0 ? bias : nullptr; e.rmw = false; }
;                   e(acc, brow, bcol, wr, wc, fr, fq); });
.LBB0_1470:
	v_lshrrev_b32_e32 v128, 1, v136
	v_and_b32_e32 v129, 0x60, v128
	v_and_b32_e32 v128, 24, v128
	v_add3_u32 v158, v129, s2, v128
	v_ashrrev_i32_e32 v159, 31, v158
	v_lshlrev_b64 v[138:139], 2, v[158:159]
	v_lshl_add_u64 v[160:161], s[46:47], 0, v[138:139]
	global_load_dwordx4 v[128:131], v[160:161], off offset:16
	global_load_dwordx4 v[132:135], v[160:161], off
	v_and_b32_e32 v137, 15, v136
	v_ashrrev_i32_e32 v136, 2, v136
	s_movk_i32 s2, 0xffc0
	v_and_or_b32 v164, v136, s2, v137
	v_ashrrev_i32_e32 v165, 31, v164
	v_lshlrev_b64 v[136:137], 12, v[164:165]
	v_lshl_add_u64 v[162:163], s[48:49], 0, v[136:137]
	v_cndmask_b32_e64 v137, 0, 1, s[14:15]
	v_lshl_add_u64 v[166:167], v[162:163], 0, v[138:139]
	v_mov_b32_e32 v136, 0
	v_cmp_ne_u32_e64 s[2:3], 1, v137
	s_and_b64 vcc, exec, s[14:15]
	s_cbranch_vccz .Lrpf_skip_1
	global_load_dword v172, v[166:167], off
	v_add_co_u32_e32 v188, vcc, 0x10000, v166
	s_nop 1
	v_addc_co_u32_e32 v189, vcc, 0, v167, vcc
	global_load_dword v173, v[188:189], off
	v_add_co_u32_e32 v188, vcc, 0x20000, v166
	s_nop 1
	v_addc_co_u32_e32 v189, vcc, 0, v167, vcc
	global_load_dword v174, v[188:189], off
	v_add_co_u32_e32 v188, vcc, 0x30000, v166
	s_nop 1
	v_addc_co_u32_e32 v189, vcc, 0, v167, vcc
	global_load_dword v175, v[188:189], off
	v_add_co_u32_e32 v188, vcc, 0x80000, v166
	s_nop 1
	v_addc_co_u32_e32 v189, vcc, 0, v167, vcc
	global_load_dword v176, v[188:189], off
	v_add_co_u32_e32 v188, vcc, 0x90000, v166
	s_nop 1
	v_addc_co_u32_e32 v189, vcc, 0, v167, vcc
	global_load_dword v177, v[188:189], off
	v_add_co_u32_e32 v188, vcc, 0xa0000, v166
	s_nop 1
	v_addc_co_u32_e32 v189, vcc, 0, v167, vcc
	global_load_dword v178, v[188:189], off
	v_add_co_u32_e32 v188, vcc, 0xb0000, v166
	s_nop 1
	v_addc_co_u32_e32 v189, vcc, 0, v167, vcc
	global_load_dword v179, v[188:189], off
	v_add_co_u32_e32 v188, vcc, 0x200, v166
	s_nop 1
	v_addc_co_u32_e32 v189, vcc, 0, v167, vcc
	global_load_dword v180, v[188:189], off
	v_add_co_u32_e32 v188, vcc, 0x10200, v166
	s_nop 1
	v_addc_co_u32_e32 v189, vcc, 0, v167, vcc
	global_load_dword v181, v[188:189], off
	v_add_co_u32_e32 v188, vcc, 0x20200, v166
	s_nop 1
	v_addc_co_u32_e32 v189, vcc, 0, v167, vcc
	global_load_dword v182, v[188:189], off
	v_add_co_u32_e32 v188, vcc, 0x30200, v166
	s_nop 1
	v_addc_co_u32_e32 v189, vcc, 0, v167, vcc
	global_load_dword v183, v[188:189], off
	v_add_co_u32_e32 v188, vcc, 0x80200, v166
	s_nop 1
	v_addc_co_u32_e32 v189, vcc, 0, v167, vcc
	global_load_dword v184, v[188:189], off
	v_add_co_u32_e32 v188, vcc, 0x90200, v166
	s_nop 1
	v_addc_co_u32_e32 v189, vcc, 0, v167, vcc
	global_load_dword v185, v[188:189], off
	v_add_co_u32_e32 v188, vcc, 0xa0200, v166
	s_nop 1
	v_addc_co_u32_e32 v189, vcc, 0, v167, vcc
	global_load_dword v186, v[188:189], off
	v_add_co_u32_e32 v188, vcc, 0xb0200, v166
	s_nop 1
	v_addc_co_u32_e32 v189, vcc, 0, v167, vcc
	global_load_dword v187, v[188:189], off

; #define EPI_LOOP_ROWS _Pragma("unroll") for (int ai = 0; ai < 2; ++ai) _Pragma("unroll") for (int m = 0; m < 4; ++m)
; #define EPI_LOOP_BJ _Pragma("unroll") for (int bj = 0; bj < 2; ++bj)
;     DI void operator()(const AccT& acc, int brow, int bcol, int wr, int wc, int fr, int fq) const {
;         EPI_LOOP_BJ { const int col = bcol + bj * 128 + wc * 32 + fq * 8;
;             const f32x4 g0 = *(const f32x4*)(gate + col), g1 = *(const f32x4*)(gate + col + 4); f32x4 b0 = (f32x4){0.f, 0.f, 0.f, 0.f}, b1 = b0; if (bias) { b0 = *(const f32x4*)(bias + col); b1 = *(const f32x4*)(bias + col + 4); }
;             EPI_LOOP_ROWS { const size_t eo = (size_t)(ai * 128 + wr * 64 + m * 16 + fr) * D + col; float* q = base + eo;
;                 f32x4 x0 = (f32x4){0.f, 0.f, 0.f, 0.f}, x1 = x0; if (rmw) { x0 = *(const f32x4*)(src + eo); x1 = *(const f32x4*)(src + eo + 4); }
;                 x0 += g0 * (acc[ai][bj][m][0] + b0); x1 += g1 * (acc[ai][bj][m][1] + b1); *(f32x4*)q = x0; *(f32x4*)(q + 4) = x1; } }
; template <int S>
; DI void gemm_resid(const bf16_t* A, const bf16_t* Bt, int K, bool with_ctx, float* out, const float* xin, const float* gate, const float* bias, float* part, char* shm) {
;     ...
;               [&](int L, const AccT& acc, int brow, int bcol, int wr, int wc, int fr, int fq) {
;                   const int b = brow / LT; EpiResid e;
;                   if (L < 256) { const size_t ro = ((size_t)(b * LL + (brow - b * LT) - LC)) * D; e.base = out + ro; e.src = xin + ro; e.gate = gate + (size_t)b * 6144; e.bias = bias; e.rmw = true; }
;                   else { const int s = (L - 256) % S; e.base = part + ((size_t)s * NB * LC + b * LC) * D; e.src = e.base; e.gate = gate + (size_t)8 * 6144; e.bias = s == 0 ? bias : nullptr; e.rmw = false; }
;                   e(acc, brow, bcol, wr, wc, fr, fq); });
.LBB0_1788:
	v_lshrrev_b32_e32 v128, 1, v136
	v_and_b32_e32 v129, 0x60, v128
	v_and_b32_e32 v128, 24, v128
	v_add3_u32 v158, v129, s71, v128
	v_ashrrev_i32_e32 v159, 31, v158
	v_lshlrev_b64 v[138:139], 2, v[158:159]
	v_lshl_add_u64 v[160:161], s[4:5], 0, v[138:139]
	global_load_dwordx4 v[128:131], v[160:161], off offset:16
	global_load_dwordx4 v[132:135], v[160:161], off
	v_and_b32_e32 v137, 15, v136
	v_ashrrev_i32_e32 v136, 2, v136
	s_movk_i32 s4, 0xffc0
	v_and_or_b32 v164, v136, s4, v137
	v_ashrrev_i32_e32 v165, 31, v164
	v_lshlrev_b64 v[136:137], 12, v[164:165]
	v_lshl_add_u64 v[162:163], s[40:41], 0, v[136:137]
	v_cndmask_b32_e64 v137, 0, 1, s[14:15]
	v_lshl_add_u64 v[166:167], v[162:163], 0, v[138:139]
	v_mov_b32_e32 v136, 0
	v_cmp_ne_u32_e64 s[4:5], 1, v137
	s_and_b64 vcc, exec, s[14:15]
	s_cbranch_vccz .Lrpf_skip_2
	global_load_dword v172, v[166:167], off
	v_add_co_u32_e32 v188, vcc, 0x10000, v166
	s_nop 1
	v_addc_co_u32_e32 v189, vcc, 0, v167, vcc
	global_load_dword v173, v[188:189], off
	v_add_co_u32_e32 v188, vcc, 0x20000, v166
	s_nop 1
	v_addc_co_u32_e32 v189, vcc, 0, v167, vcc
	global_load_dword v174, v[188:189], off
	v_add_co_u32_e32 v188, vcc, 0x30000, v166
	s_nop 1
	v_addc_co_u32_e32 v189, vcc, 0, v167, vcc
	global_load_dword v175, v[188:189], off
	v_add_co_u32_e32 v188, vcc, 0x80000, v166
	s_nop 1
	v_addc_co_u32_e32 v189, vcc, 0, v167, vcc
	global_load_dword v176, v[188:189], off
	v_add_co_u32_e32 v188, vcc, 0x90000, v166
	s_nop 1
	v_addc_co_u32_e32 v189, vcc, 0, v167, vcc
	global_load_dword v177, v[188:189], off
	v_add_co_u32_e32 v188, vcc, 0xa0000, v166
	s_nop 1
	v_addc_co_u32_e32 v189, vcc, 0, v167, vcc
	global_load_dword v178, v[188:189], off
	v_add_co_u32_e32 v188, vcc, 0xb0000, v166
	s_nop 1
	v_addc_co_u32_e32 v189, vcc, 0, v167, vcc
	global_load_dword v179, v[188:189], off
	v_add_co_u32_e32 v188, vcc, 0x200, v166
	s_nop 1
	v_addc_co_u32_e32 v189, vcc, 0, v167, vcc
	global_load_dword v180, v[188:189], off
	v_add_co_u32_e32 v188, vcc, 0x10200, v166
	s_nop 1
	v_addc_co_u32_e32 v189, vcc, 0, v167, vcc
	global_load_dword v181, v[188:189], off
	v_add_co_u32_e32 v188, vcc, 0x20200, v166
	s_nop 1
	v_addc_co_u32_e32 v189, vcc, 0, v167, vcc
	global_load_dword v182, v[188:189], off
	v_add_co_u32_e32 v188, vcc, 0x30200, v166
	s_nop 1
	v_addc_co_u32_e32 v189, vcc, 0, v167, vcc
	global_load_dword v183, v[188:189], off
	v_add_co_u32_e32 v188, vcc, 0x80200, v166
	s_nop 1
	v_addc_co_u32_e32 v189, vcc, 0, v167, vcc
	global_load_dword v184, v[188:189], off
	v_add_co_u32_e32 v188, vcc, 0x90200, v166
	s_nop 1
	v_addc_co_u32_e32 v189, vcc, 0, v167, vcc
	global_load_dword v185, v[188:189], off
	v_add_co_u32_e32 v188, vcc, 0xa0200, v166
	s_nop 1
	v_addc_co_u32_e32 v189, vcc, 0, v167, vcc
	global_load_dword v186, v[188:189], off
	v_add_co_u32_e32 v188, vcc, 0xb0200, v166
	s_nop 1
	v_addc_co_u32_e32 v189, vcc, 0, v167, vcc
	global_load_dword v187, v[188:189], off

; #define EPI_LOOP_ROWS _Pragma("unroll") for (int ai = 0; ai < 2; ++ai) _Pragma("unroll") for (int m = 0; m < 4; ++m)
; #define EPI_LOOP_BJ _Pragma("unroll") for (int bj = 0; bj < 2; ++bj)
;     DI void operator()(const AccT& acc, int brow, int bcol, int wr, int wc, int fr, int fq) const {
;         EPI_LOOP_BJ { const int col = bcol + bj * 128 + wc * 32 + fq * 8;
;             const f32x4 g0 = *(const f32x4*)(gate + col), g1 = *(const f32x4*)(gate + col + 4); f32x4 b0 = (f32x4){0.f, 0.f, 0.f, 0.f}, b1 = b0; if (bias) { b0 = *(const f32x4*)(bias + col); b1 = *(const f32x4*)(bias + col + 4); }
;             EPI_LOOP_ROWS { const size_t eo = (size_t)(ai * 128 + wr * 64 + m * 16 + fr) * D + col; float* q = base + eo;
;                 f32x4 x0 = (f32x4){0.f, 0.f, 0.f, 0.f}, x1 = x0; if (rmw) { x0 = *(const f32x4*)(src + eo); x1 = *(const f32x4*)(src + eo + 4); }
;                 x0 += g0 * (acc[ai][bj][m][0] + b0); x1 += g1 * (acc[ai][bj][m][1] + b1); *(f32x4*)q = x0; *(f32x4*)(q + 4) = x1; } }
; template <int S>
; DI void gemm_resid(const bf16_t* A, const bf16_t* Bt, int K, bool with_ctx, float* out, const float* xin, const float* gate, const float* bias, float* part, char* shm) {
;     ...
;               [&](int L, const AccT& acc, int brow, int bcol, int wr, int wc, int fr, int fq) {
;                   const int b = brow / LT; EpiResid e;
;                   if (L < 256) { const size_t ro = ((size_t)(b * LL + (brow - b * LT) - LC)) * D; e.base = out + ro; e.src = xin + ro; e.gate = gate + (size_t)b * 6144; e.bias = bias; e.rmw = true; }
;                   else { const int s = (L - 256) % S; e.base = part + ((size_t)s * NB * LC + b * LC) * D; e.src = e.base; e.gate = gate + (size_t)8 * 6144; e.bias = s == 0 ? bias : nullptr; e.rmw = false; }
;                   e(acc, brow, bcol, wr, wc, fr, fq); });
.LBB0_2581:
	v_lshrrev_b32_e32 v128, 1, v136
	v_and_b32_e32 v129, 0x60, v128
	v_and_b32_e32 v128, 24, v128
	v_add3_u32 v158, v129, s2, v128
	v_ashrrev_i32_e32 v159, 31, v158
	v_lshlrev_b64 v[138:139], 2, v[158:159]
	v_lshl_add_u64 v[160:161], s[46:47], 0, v[138:139]
	global_load_dwordx4 v[128:131], v[160:161], off offset:16
	global_load_dwordx4 v[132:135], v[160:161], off
	v_and_b32_e32 v137, 15, v136
	v_ashrrev_i32_e32 v136, 2, v136
	s_movk_i32 s2, 0xffc0
	v_and_or_b32 v164, v136, s2, v137
	v_ashrrev_i32_e32 v165, 31, v164
	v_lshlrev_b64 v[136:137], 12, v[164:165]
	v_lshl_add_u64 v[162:163], s[52:53], 0, v[136:137]
	v_cndmask_b32_e64 v137, 0, 1, s[14:15]
	v_lshl_add_u64 v[166:167], v[162:163], 0, v[138:139]
	v_mov_b32_e32 v136, 0
	v_cmp_ne_u32_e64 s[2:3], 1, v137
	s_and_b64 vcc, exec, s[14:15]
	s_cbranch_vccz .Lrpf_skip_3
	global_load_dword v172, v[166:167], off
	v_add_co_u32_e32 v188, vcc, 0x10000, v166
	s_nop 1
	v_addc_co_u32_e32 v189, vcc, 0, v167, vcc
	global_load_dword v173, v[188:189], off
	v_add_co_u32_e32 v188, vcc, 0x20000, v166
	s_nop 1
	v_addc_co_u32_e32 v189, vcc, 0, v167, vcc
	global_load_dword v174, v[188:189], off
	v_add_co_u32_e32 v188, vcc, 0x30000, v166
	s_nop 1
	v_addc_co_u32_e32 v189, vcc, 0, v167, vcc
	global_load_dword v175, v[188:189], off
	v_add_co_u32_e32 v188, vcc, 0x80000, v166
	s_nop 1
	v_addc_co_u32_e32 v189, vcc, 0, v167, vcc
	global_load_dword v176, v[188:189], off
	v_add_co_u32_e32 v188, vcc, 0x90000, v166
	s_nop 1
	v_addc_co_u32_e32 v189, vcc, 0, v167, vcc
	global_load_dword v177, v[188:189], off
	v_add_co_u32_e32 v188, vcc, 0xa0000, v166
	s_nop 1
	v_addc_co_u32_e32 v189, vcc, 0, v167, vcc
	global_load_dword v178, v[188:189], off
	v_add_co_u32_e32 v188, vcc, 0xb0000, v166
	s_nop 1
	v_addc_co_u32_e32 v189, vcc, 0, v167, vcc
	global_load_dword v179, v[188:189], off
	v_add_co_u32_e32 v188, vcc, 0x200, v166
	s_nop 1
	v_addc_co_u32_e32 v189, vcc, 0, v167, vcc
	global_load_dword v180, v[188:189], off
	v_add_co_u32_e32 v188, vcc, 0x10200, v166
	s_nop 1
	v_addc_co_u32_e32 v189, vcc, 0, v167, vcc
	global_load_dword v181, v[188:189], off
	v_add_co_u32_e32 v188, vcc, 0x20200, v166
	s_nop 1
	v_addc_co_u32_e32 v189, vcc, 0, v167, vcc
	global_load_dword v182, v[188:189], off
	v_add_co_u32_e32 v188, vcc, 0x30200, v166
	s_nop 1
	v_addc_co_u32_e32 v189, vcc, 0, v167, vcc
	global_load_dword v183, v[188:189], off
	v_add_co_u32_e32 v188, vcc, 0x80200, v166
	s_nop 1
	v_addc_co_u32_e32 v189, vcc, 0, v167, vcc
	global_load_dword v184, v[188:189], off
	v_add_co_u32_e32 v188, vcc, 0x90200, v166
	s_nop 1
	v_addc_co_u32_e32 v189, vcc, 0, v167, vcc
	global_load_dword v185, v[188:189], off
	v_add_co_u32_e32 v188, vcc, 0xa0200, v166
	s_nop 1
	v_addc_co_u32_e32 v189, vcc, 0, v167, vcc
	global_load_dword v186, v[188:189], off
	v_add_co_u32_e32 v188, vcc, 0xb0200, v166
	s_nop 1
	v_addc_co_u32_e32 v189, vcc, 0, v167, vcc
	global_load_dword v187, v[188:189], off

; #define EPI_LOOP_ROWS _Pragma("unroll") for (int ai = 0; ai < 2; ++ai) _Pragma("unroll") for (int m = 0; m < 4; ++m)
; #define EPI_LOOP_BJ _Pragma("unroll") for (int bj = 0; bj < 2; ++bj)
;     DI void operator()(const AccT& acc, int brow, int bcol, int wr, int wc, int fr, int fq) const {
;         EPI_LOOP_BJ { const int col = bcol + bj * 128 + wc * 32 + fq * 8;
;             const f32x4 g0 = *(const f32x4*)(gate + col), g1 = *(const f32x4*)(gate + col + 4); f32x4 b0 = (f32x4){0.f, 0.f, 0.f, 0.f}, b1 = b0; if (bias) { b0 = *(const f32x4*)(bias + col); b1 = *(const f32x4*)(bias + col + 4); }
;             EPI_LOOP_ROWS { const size_t eo = (size_t)(ai * 128 + wr * 64 + m * 16 + fr) * D + col; float* q = base + eo;
;                 f32x4 x0 = (f32x4){0.f, 0.f, 0.f, 0.f}, x1 = x0; if (rmw) { x0 = *(const f32x4*)(src + eo); x1 = *(const f32x4*)(src + eo + 4); }
;                 x0 += g0 * (acc[ai][bj][m][0] + b0); x1 += g1 * (acc[ai][bj][m][1] + b1); *(f32x4*)q = x0; *(f32x4*)(q + 4) = x1; } }
; template <int S>
; DI void gemm_resid(const bf16_t* A, const bf16_t* Bt, int K, bool with_ctx, float* out, const float* xin, const float* gate, const float* bias, float* part, char* shm) {
;     ...
;               [&](int L, const AccT& acc, int brow, int bcol, int wr, int wc, int fr, int fq) {
;                   const int b = brow / LT; EpiResid e;
;                   if (L < 256) { const size_t ro = ((size_t)(b * LL + (brow - b * LT) - LC)) * D; e.base = out + ro; e.src = xin + ro; e.gate = gate + (size_t)b * 6144; e.bias = bias; e.rmw = true; }
;                   else { const int s = (L - 256) % S; e.base = part + ((size_t)s * NB * LC + b * LC) * D; e.src = e.base; e.gate = gate + (size_t)8 * 6144; e.bias = s == 0 ? bias : nullptr; e.rmw = false; }
;                   e(acc, brow, bcol, wr, wc, fr, fq); });
.LBB0_2899:
	v_lshrrev_b32_e32 v128, 1, v136
	v_and_b32_e32 v129, 0x60, v128
	v_and_b32_e32 v128, 24, v128
	v_add3_u32 v158, v129, s77, v128
	v_ashrrev_i32_e32 v159, 31, v158
	v_lshlrev_b64 v[138:139], 2, v[158:159]
	v_lshl_add_u64 v[160:161], s[4:5], 0, v[138:139]
	global_load_dwordx4 v[128:131], v[160:161], off offset:16
	global_load_dwordx4 v[132:135], v[160:161], off
	v_and_b32_e32 v137, 15, v136
	v_ashrrev_i32_e32 v136, 2, v136
	v_and_or_b32 v164, v136, s71, v137
	v_ashrrev_i32_e32 v165, 31, v164
	v_lshlrev_b64 v[136:137], 12, v[164:165]
	v_lshl_add_u64 v[162:163], s[44:45], 0, v[136:137]
	v_cndmask_b32_e64 v137, 0, 1, s[14:15]
	v_lshl_add_u64 v[166:167], v[162:163], 0, v[138:139]
	v_mov_b32_e32 v136, 0
	v_cmp_ne_u32_e64 s[4:5], 1, v137
	s_and_b64 vcc, exec, s[14:15]
	s_cbranch_vccz .Lrpf_skip_4
	global_load_dword v172, v[166:167], off
	v_add_co_u32_e32 v188, vcc, 0x10000, v166
	s_nop 1
	v_addc_co_u32_e32 v189, vcc, 0, v167, vcc
	global_load_dword v173, v[188:189], off
	v_add_co_u32_e32 v188, vcc, 0x20000, v166
	s_nop 1
	v_addc_co_u32_e32 v189, vcc, 0, v167, vcc
	global_load_dword v174, v[188:189], off
	v_add_co_u32_e32 v188, vcc, 0x30000, v166
	s_nop 1
	v_addc_co_u32_e32 v189, vcc, 0, v167, vcc
	global_load_dword v175, v[188:189], off
	v_add_co_u32_e32 v188, vcc, 0x80000, v166
	s_nop 1
	v_addc_co_u32_e32 v189, vcc, 0, v167, vcc
	global_load_dword v176, v[188:189], off
	v_add_co_u32_e32 v188, vcc, 0x90000, v166
	s_nop 1
	v_addc_co_u32_e32 v189, vcc, 0, v167, vcc
	global_load_dword v177, v[188:189], off
	v_add_co_u32_e32 v188, vcc, 0xa0000, v166
	s_nop 1
	v_addc_co_u32_e32 v189, vcc, 0, v167, vcc
	global_load_dword v178, v[188:189], off
	v_add_co_u32_e32 v188, vcc, 0xb0000, v166
	s_nop 1
	v_addc_co_u32_e32 v189, vcc, 0, v167, vcc
	global_load_dword v179, v[188:189], off
	v_add_co_u32_e32 v188, vcc, 0x200, v166
	s_nop 1
	v_addc_co_u32_e32 v189, vcc, 0, v167, vcc
	global_load_dword v180, v[188:189], off
	v_add_co_u32_e32 v188, vcc, 0x10200, v166
	s_nop 1
	v_addc_co_u32_e32 v189, vcc, 0, v167, vcc
	global_load_dword v181, v[188:189], off
	v_add_co_u32_e32 v188, vcc, 0x20200, v166
	s_nop 1
	v_addc_co_u32_e32 v189, vcc, 0, v167, vcc
	global_load_dword v182, v[188:189], off
	v_add_co_u32_e32 v188, vcc, 0x30200, v166
	s_nop 1
	v_addc_co_u32_e32 v189, vcc, 0, v167, vcc
	global_load_dword v183, v[188:189], off
	v_add_co_u32_e32 v188, vcc, 0x80200, v166
	s_nop 1
	v_addc_co_u32_e32 v189, vcc, 0, v167, vcc
	global_load_dword v184, v[188:189], off
	v_add_co_u32_e32 v188, vcc, 0x90200, v166
	s_nop 1
	v_addc_co_u32_e32 v189, vcc, 0, v167, vcc
	global_load_dword v185, v[188:189], off
	v_add_co_u32_e32 v188, vcc, 0xa0200, v166
	s_nop 1
	v_addc_co_u32_e32 v189, vcc, 0, v167, vcc
	global_load_dword v186, v[188:189], off
	v_add_co_u32_e32 v188, vcc, 0xb0200, v166
	s_nop 1
	v_addc_co_u32_e32 v189, vcc, 0, v167, vcc
	global_load_dword v187, v[188:189], off

; #define EPI_LOOP_ROWS _Pragma("unroll") for (int ai = 0; ai < 2; ++ai) _Pragma("unroll") for (int m = 0; m < 4; ++m)
; #define EPI_LOOP_BJ _Pragma("unroll") for (int bj = 0; bj < 2; ++bj)
;     DI void operator()(const AccT& acc, int brow, int bcol, int wr, int wc, int fr, int fq) const {
;         EPI_LOOP_BJ { const int col = bcol + bj * 128 + wc * 32 + fq * 8;
;             const f32x4 g0 = *(const f32x4*)(gate + col), g1 = *(const f32x4*)(gate + col + 4); f32x4 b0 = (f32x4){0.f, 0.f, 0.f, 0.f}, b1 = b0; if (bias) { b0 = *(const f32x4*)(bias + col); b1 = *(const f32x4*)(bias + col + 4); }
;             EPI_LOOP_ROWS { const size_t eo = (size_t)(ai * 128 + wr * 64 + m * 16 + fr) * D + col; float* q = base + eo;
;                 f32x4 x0 = (f32x4){0.f, 0.f, 0.f, 0.f}, x1 = x0; if (rmw) { x0 = *(const f32x4*)(src + eo); x1 = *(const f32x4*)(src + eo + 4); }
;                 x0 += g0 * (acc[ai][bj][m][0] + b0); x1 += g1 * (acc[ai][bj][m][1] + b1); *(f32x4*)q = x0; *(f32x4*)(q + 4) = x1; } }
; template <int S>
; DI void gemm_resid(const bf16_t* A, const bf16_t* Bt, int K, bool with_ctx, float* out, const float* xin, const float* gate, const float* bias, float* part, char* shm) {
;     ...
;               [&](int L, const AccT& acc, int brow, int bcol, int wr, int wc, int fr, int fq) {
;                   const int b = brow / LT; EpiResid e;
;                   if (L < 256) { const size_t ro = ((size_t)(b * LL + (brow - b * LT) - LC)) * D; e.base = out + ro; e.src = xin + ro; e.gate = gate + (size_t)b * 6144; e.bias = bias; e.rmw = true; }
;                   else { const int s = (L - 256) % S; e.base = part + ((size_t)s * NB * LC + b * LC) * D; e.src = e.base; e.gate = gate + (size_t)8 * 6144; e.bias = s == 0 ? bias : nullptr; e.rmw = false; }
;                   e(acc, brow, bcol, wr, wc, fr, fq); });
.LBB0_3473:
	v_lshrrev_b32_e32 v128, 1, v136
	v_and_b32_e32 v129, 0x60, v128
	v_and_b32_e32 v128, 24, v128
	v_add3_u32 v158, v129, s2, v128
	v_ashrrev_i32_e32 v159, 31, v158
	v_lshlrev_b64 v[138:139], 2, v[158:159]
	v_lshl_add_u64 v[160:161], s[46:47], 0, v[138:139]
	global_load_dwordx4 v[128:131], v[160:161], off offset:16
	global_load_dwordx4 v[132:135], v[160:161], off
	v_and_b32_e32 v137, 15, v136
	v_ashrrev_i32_e32 v136, 2, v136
	v_and_or_b32 v164, v136, s58, v137
	v_ashrrev_i32_e32 v165, 31, v164
	v_lshlrev_b64 v[136:137], 12, v[164:165]
	v_lshl_add_u64 v[162:163], s[44:45], 0, v[136:137]
	v_cndmask_b32_e64 v137, 0, 1, s[14:15]
	v_lshl_add_u64 v[166:167], v[162:163], 0, v[138:139]
	v_mov_b32_e32 v136, 0
	v_cmp_ne_u32_e64 s[2:3], 1, v137
	s_and_b64 vcc, exec, s[14:15]
	s_cbranch_vccz .Lrpf_skip_5
	global_load_dword v172, v[166:167], off
	v_add_co_u32_e32 v188, vcc, 0x10000, v166
	s_nop 1
	v_addc_co_u32_e32 v189, vcc, 0, v167, vcc
	global_load_dword v173, v[188:189], off
	v_add_co_u32_e32 v188, vcc, 0x20000, v166
	s_nop 1
	v_addc_co_u32_e32 v189, vcc, 0, v167, vcc
	global_load_dword v174, v[188:189], off
	v_add_co_u32_e32 v188, vcc, 0x30000, v166
	s_nop 1
	v_addc_co_u32_e32 v189, vcc, 0, v167, vcc
	global_load_dword v175, v[188:189], off
	v_add_co_u32_e32 v188, vcc, 0x80000, v166
	s_nop 1
	v_addc_co_u32_e32 v189, vcc, 0, v167, vcc
	global_load_dword v176, v[188:189], off
	v_add_co_u32_e32 v188, vcc, 0x90000, v166
	s_nop 1
	v_addc_co_u32_e32 v189, vcc, 0, v167, vcc
	global_load_dword v177, v[188:189], off
	v_add_co_u32_e32 v188, vcc, 0xa0000, v166
	s_nop 1
	v_addc_co_u32_e32 v189, vcc, 0, v167, vcc
	global_load_dword v178, v[188:189], off
	v_add_co_u32_e32 v188, vcc, 0xb0000, v166
	s_nop 1
	v_addc_co_u32_e32 v189, vcc, 0, v167, vcc
	global_load_dword v179, v[188:189], off
	v_add_co_u32_e32 v188, vcc, 0x200, v166
	s_nop 1
	v_addc_co_u32_e32 v189, vcc, 0, v167, vcc
	global_load_dword v180, v[188:189], off
	v_add_co_u32_e32 v188, vcc, 0x10200, v166
	s_nop 1
	v_addc_co_u32_e32 v189, vcc, 0, v167, vcc
	global_load_dword v181, v[188:189], off
	v_add_co_u32_e32 v188, vcc, 0x20200, v166
	s_nop 1
	v_addc_co_u32_e32 v189, vcc, 0, v167, vcc
	global_load_dword v182, v[188:189], off
	v_add_co_u32_e32 v188, vcc, 0x30200, v166
	s_nop 1
	v_addc_co_u32_e32 v189, vcc, 0, v167, vcc
	global_load_dword v183, v[188:189], off
	v_add_co_u32_e32 v188, vcc, 0x80200, v166
	s_nop 1
	v_addc_co_u32_e32 v189, vcc, 0, v167, vcc
	global_load_dword v184, v[188:189], off
	v_add_co_u32_e32 v188, vcc, 0x90200, v166
	s_nop 1
	v_addc_co_u32_e32 v189, vcc, 0, v167, vcc
	global_load_dword v185, v[188:189], off
	v_add_co_u32_e32 v188, vcc, 0xa0200, v166
	s_nop 1
	v_addc_co_u32_e32 v189, vcc, 0, v167, vcc
	global_load_dword v186, v[188:189], off
	v_add_co_u32_e32 v188, vcc, 0xb0200, v166
	s_nop 1
	v_addc_co_u32_e32 v189, vcc, 0, v167, vcc
	global_load_dword v187, v[188:189], off

; #define EPI_LOOP_ROWS _Pragma("unroll") for (int ai = 0; ai < 2; ++ai) _Pragma("unroll") for (int m = 0; m < 4; ++m)
; #define EPI_LOOP_BJ _Pragma("unroll") for (int bj = 0; bj < 2; ++bj)
;     DI void operator()(const AccT& acc, int brow, int bcol, int wr, int wc, int fr, int fq) const {
;         EPI_LOOP_BJ { const int col = bcol + bj * 128 + wc * 32 + fq * 8;
;             const f32x4 g0 = *(const f32x4*)(gate + col), g1 = *(const f32x4*)(gate + col + 4); f32x4 b0 = (f32x4){0.f, 0.f, 0.f, 0.f}, b1 = b0; if (bias) { b0 = *(const f32x4*)(bias + col); b1 = *(const f32x4*)(bias + col + 4); }
;             EPI_LOOP_ROWS { const size_t eo = (size_t)(ai * 128 + wr * 64 + m * 16 + fr) * D + col; float* q = base + eo;
;                 f32x4 x0 = (f32x4){0.f, 0.f, 0.f, 0.f}, x1 = x0; if (rmw) { x0 = *(const f32x4*)(src + eo); x1 = *(const f32x4*)(src + eo + 4); }
.LBB0_3766:
	v_lshrrev_b32_e32 v128, 1, v136
	v_and_b32_e32 v129, 0x60, v128
	v_and_b32_e32 v128, 24, v128
	v_add3_u32 v158, v129, s51, v128
	v_ashrrev_i32_e32 v159, 31, v158
	v_lshlrev_b64 v[138:139], 2, v[158:159]
	v_lshl_add_u64 v[160:161], s[2:3], 0, v[138:139]
	global_load_dwordx4 v[128:131], v[160:161], off offset:16
	global_load_dwordx4 v[132:135], v[160:161], off
	v_and_b32_e32 v137, 15, v136
	v_ashrrev_i32_e32 v136, 2, v136
	v_and_or_b32 v164, v136, s46, v137
	v_ashrrev_i32_e32 v165, 31, v164
	v_lshlrev_b64 v[136:137], 12, v[164:165]
	v_lshl_add_u64 v[162:163], s[24:25], 0, v[136:137]
	v_cndmask_b32_e64 v137, 0, 1, s[30:31]
	v_lshl_add_u64 v[166:167], v[162:163], 0, v[138:139]
	v_mov_b32_e32 v136, 0
	v_cmp_ne_u32_e64 s[2:3], 1, v137
	s_and_b64 vcc, exec, s[30:31]
	s_cbranch_vccz .Lrpf_skip_6
	global_load_dword v172, v[166:167], off
	v_add_co_u32_e32 v188, vcc, 0x10000, v166
	s_nop 1
	v_addc_co_u32_e32 v189, vcc, 0, v167, vcc
	global_load_dword v173, v[188:189], off
	v_add_co_u32_e32 v188, vcc, 0x20000, v166
	s_nop 1
	v_addc_co_u32_e32 v189, vcc, 0, v167, vcc
	global_load_dword v174, v[188:189], off
	v_add_co_u32_e32 v188, vcc, 0x30000, v166
	s_nop 1
	v_addc_co_u32_e32 v189, vcc, 0, v167, vcc
	global_load_dword v175, v[188:189], off
	v_add_co_u32_e32 v188, vcc, 0x80000, v166
	s_nop 1
	v_addc_co_u32_e32 v189, vcc, 0, v167, vcc
	global_load_dword v176, v[188:189], off
	v_add_co_u32_e32 v188, vcc, 0x90000, v166
	s_nop 1
	v_addc_co_u32_e32 v189, vcc, 0, v167, vcc
	global_load_dword v177, v[188:189], off
	v_add_co_u32_e32 v188, vcc, 0xa0000, v166
	s_nop 1
	v_addc_co_u32_e32 v189, vcc, 0, v167, vcc
	global_load_dword v178, v[188:189], off
	v_add_co_u32_e32 v188, vcc, 0xb0000, v166
	s_nop 1
	v_addc_co_u32_e32 v189, vcc, 0, v167, vcc
	global_load_dword v179, v[188:189], off
	v_add_co_u32_e32 v188, vcc, 0x200, v166
	s_nop 1
	v_addc_co_u32_e32 v189, vcc, 0, v167, vcc
	global_load_dword v180, v[188:189], off
	v_add_co_u32_e32 v188, vcc, 0x10200, v166
	s_nop 1
	v_addc_co_u32_e32 v189, vcc, 0, v167, vcc
	global_load_dword v181, v[188:189], off
	v_add_co_u32_e32 v188, vcc, 0x20200, v166
	s_nop 1
	v_addc_co_u32_e32 v189, vcc, 0, v167, vcc
	global_load_dword v182, v[188:189], off
	v_add_co_u32_e32 v188, vcc, 0x30200, v166
	s_nop 1
	v_addc_co_u32_e32 v189, vcc, 0, v167, vcc
	global_load_dword v183, v[188:189], off
	v_add_co_u32_e32 v188, vcc, 0x80200, v166
	s_nop 1
	v_addc_co_u32_e32 v189, vcc, 0, v167, vcc
	global_load_dword v184, v[188:189], off
	v_add_co_u32_e32 v188, vcc, 0x90200, v166
	s_nop 1
	v_addc_co_u32_e32 v189, vcc, 0, v167, vcc
	global_load_dword v185, v[188:189], off
	v_add_co_u32_e32 v188, vcc, 0xa0200, v166
	s_nop 1
	v_addc_co_u32_e32 v189, vcc, 0, v167, vcc
	global_load_dword v186, v[188:189], off
	v_add_co_u32_e32 v188, vcc, 0xb0200, v166
	s_nop 1
	v_addc_co_u32_e32 v189, vcc, 0, v167, vcc
	global_load_dword v187, v[188:189], off
.Lrpf_skip_6:
	s_andn2_b64 vcc, exec, s[30:31]
	v_mov_b32_e32 v142, 0
	v_mov_b32_e32 v143, 0
	v_mov_b32_e32 v144, 0
	v_mov_b32_e32 v145, 0
	v_mov_b32_e32 v138, 0
	v_mov_b32_e32 v139, 0
	v_mov_b32_e32 v140, 0
	v_mov_b32_e32 v141, 0
	s_cbranch_vccnz .LBB0_3768
	global_load_dwordx4 v[142:145], v[166:167], off
	global_load_dwordx4 v[138:141], v[166:167], off offset:16
